# v12 + phase D QK/PV gathers: 32-bit offsets on an SGPR base; next tile's indices prepared before the waits and each buffer quad refilled right after its LDS write (8 loads stay in flight)
# speedup vs baseline: 1.0492x; 1.0115x over previous
.LBB0_779:
	s_cmp_gt_u32 s22, 14
	v_lshlrev_b32_e32 v64, 1, v146
	s_cbranch_scc1 .Lqk_last
	s_add_i32 s20, s24, s2
	s_and_b32 s20, s20, 0xe0
	v_lshl_add_u32 v82, s20, 1, v72
	ds_read_u16 v83, v82
	ds_read_u16 v84, v82 offset:8
	ds_read_u16 v85, v82 offset:16
	ds_read_u16 v86, v82 offset:24
	ds_read_u16 v87, v82 offset:32
	ds_read_u16 v88, v82 offset:40
	ds_read_u16 v89, v82 offset:48
	ds_read_u16 v90, v82 offset:56
	s_and_b32 s20, s23, 0x180
	s_lshl_b32 s46, s20, 1
	v_add_u32_e32 v136, s46, v64
	s_waitcnt lgkmcnt(0)
	v_lshl_add_u32 v83, v83, 9, v136
	v_lshl_add_u32 v84, v84, 9, v136
	v_lshl_add_u32 v85, v85, 9, v136
	v_lshl_add_u32 v86, v86, 9, v136
	v_lshl_add_u32 v87, v87, 9, v136
	v_lshl_add_u32 v88, v88, 9, v136
	v_lshl_add_u32 v89, v89, 9, v136
	v_lshl_add_u32 v90, v90, 9, v136
	s_waitcnt vmcnt(7)
	ds_write_b128 v73, v[0:3] offset:8192
	global_load_dwordx4 v[0:3], v83, s[48:49]
	s_waitcnt vmcnt(7)
	ds_write_b128 v74, v[4:7] offset:9216
	global_load_dwordx4 v[4:7], v84, s[48:49]
	s_waitcnt vmcnt(7)
	ds_write_b128 v75, v[8:11] offset:10240
	global_load_dwordx4 v[8:11], v85, s[48:49]
	s_waitcnt vmcnt(7)
	ds_write_b128 v76, v[12:15] offset:11264
	global_load_dwordx4 v[12:15], v86, s[48:49]
	s_waitcnt vmcnt(7)
	ds_write_b128 v73, v[16:19] offset:12288
	global_load_dwordx4 v[16:19], v87, s[48:49]
	s_waitcnt vmcnt(7)
	ds_write_b128 v74, v[20:23] offset:13312
	global_load_dwordx4 v[20:23], v88, s[48:49]
	s_waitcnt vmcnt(7)
	ds_write_b128 v75, v[24:27] offset:14336
	global_load_dwordx4 v[24:27], v89, s[48:49]
	s_waitcnt vmcnt(7)
	ds_write_b128 v76, v[36:39] offset:15360
	global_load_dwordx4 v[36:39], v90, s[48:49]
	s_branch .LBB0_781
.Lqk_last:
	s_waitcnt vmcnt(7)
	ds_write_b128 v73, v[0:3] offset:8192
	s_waitcnt vmcnt(6)
	ds_write_b128 v74, v[4:7] offset:9216
	s_waitcnt vmcnt(5)
	ds_write_b128 v75, v[8:11] offset:10240
	s_waitcnt vmcnt(4)
	ds_write_b128 v76, v[12:15] offset:11264
	s_waitcnt vmcnt(3)
	ds_write_b128 v73, v[16:19] offset:12288
	s_waitcnt vmcnt(2)
	ds_write_b128 v74, v[20:23] offset:13312
	s_waitcnt vmcnt(1)
	ds_write_b128 v75, v[24:27] offset:14336
	s_waitcnt vmcnt(0)
	ds_write_b128 v76, v[36:39] offset:15360

.LBB0_789:
	s_cmp_gt_u32 s20, 14
	s_cbranch_scc1 .Lpv_last
	s_and_b32 s24, s22, 0xe0
	v_lshl_add_u32 v110, s24, 1, v72
	ds_read_u16 v111, v110
	ds_read_u16 v112, v110 offset:8
	ds_read_u16 v113, v110 offset:16
	ds_read_u16 v114, v110 offset:24
	ds_read_u16 v115, v110 offset:32
	ds_read_u16 v116, v110 offset:40
	ds_read_u16 v117, v110 offset:48
	ds_read_u16 v118, v110 offset:56
	s_and_b32 s24, s21, 0x180
	s_lshl_b32 s46, s24, 1
	v_add_u32_e32 v136, s46, v64
	s_waitcnt lgkmcnt(0)
	v_lshl_add_u32 v111, v111, 9, v136
	v_lshl_add_u32 v112, v112, 9, v136
	v_lshl_add_u32 v113, v113, 9, v136
	v_lshl_add_u32 v114, v114, 9, v136
	v_lshl_add_u32 v115, v115, 9, v136
	v_lshl_add_u32 v116, v116, 9, v136
	v_lshl_add_u32 v117, v117, 9, v136
	v_lshl_add_u32 v118, v118, 9, v136
	s_waitcnt vmcnt(7)
	ds_write_b128 v73, v[0:3] offset:8192
	global_load_dwordx4 v[0:3], v111, s[54:55]
	s_waitcnt vmcnt(7)
	ds_write_b128 v74, v[4:7] offset:9216
	global_load_dwordx4 v[4:7], v112, s[54:55]
	s_waitcnt vmcnt(7)
	ds_write_b128 v75, v[8:11] offset:10240
	global_load_dwordx4 v[8:11], v113, s[54:55]
	s_waitcnt vmcnt(7)
	ds_write_b128 v76, v[12:15] offset:11264
	global_load_dwordx4 v[12:15], v114, s[54:55]
	s_waitcnt vmcnt(7)
	ds_write_b128 v73, v[16:19] offset:12288
	global_load_dwordx4 v[16:19], v115, s[54:55]
	s_waitcnt vmcnt(7)
	ds_write_b128 v74, v[20:23] offset:13312
	global_load_dwordx4 v[20:23], v116, s[54:55]
	s_waitcnt vmcnt(7)
	ds_write_b128 v75, v[24:27] offset:14336
	global_load_dwordx4 v[24:27], v117, s[54:55]
	s_waitcnt vmcnt(7)
	ds_write_b128 v76, v[28:31] offset:15360
	global_load_dwordx4 v[28:31], v118, s[54:55]
	s_branch .LBB0_788
.Lpv_last:
	s_waitcnt vmcnt(7)
	ds_write_b128 v73, v[0:3] offset:8192
	s_waitcnt vmcnt(6)
	ds_write_b128 v74, v[4:7] offset:9216
	s_waitcnt vmcnt(5)
	ds_write_b128 v75, v[8:11] offset:10240
	s_waitcnt vmcnt(4)
	ds_write_b128 v76, v[12:15] offset:11264
	s_waitcnt vmcnt(3)
	ds_write_b128 v73, v[16:19] offset:12288
	s_waitcnt vmcnt(2)
	ds_write_b128 v74, v[20:23] offset:13312
	s_waitcnt vmcnt(1)
	ds_write_b128 v75, v[24:27] offset:14336
	s_waitcnt vmcnt(0)
	ds_write_b128 v76, v[28:31] offset:15360
	s_branch .LBB0_788
